# swiglu epilogue switched to packed f32 math (v_pk_mul/add) with the lane-transposed stores
# speedup vs baseline: 1.0103x; 1.0008x over previous
; __device__ __forceinline__ unsigned pk2(float lo, float hi) { return pg8::cvt_pk_bf16(lo, hi); }
; __device__ __forceinline__ float siluf_(float x) { return x * sigmoidf_(x); }
;     __device__ __forceinline__ void operator()(const f32x4 (&acc)[2][2][4][2], const pg8::Unit& u, int wr, int wc, int fr, int fq) const {
;         const int row0 = u.pm * 256 + wr * 64 + fr, col0 = u.pn * 128 + wc * 32 + 8 * fq;
; #pragma unroll
;         for (int ai = 0; ai < 2; ++ai)
; #pragma unroll
;             for (int m = 0; m < 4; ++m) {
;                 bf16_t* rowp = O + (size_t)(row0 + ai * 128 + m * 16) * ldc + col0;
;                 const f32x4 a0 = acc[ai][0][m][0], a1 = acc[ai][0][m][1], g0 = acc[ai][1][m][0], g1 = acc[ai][1][m][1];
;                 u32x4 w;
;                 w.x = pk2(siluf_(a0[0]) * g0[0], siluf_(a0[1]) * g0[1]); w.y = pk2(siluf_(a0[2]) * g0[2], siluf_(a0[3]) * g0[3]);
;                 w.z = pk2(siluf_(a1[0]) * g1[0], siluf_(a1[1]) * g1[1]); w.w = pk2(siluf_(a1[2]) * g1[2], siluf_(a1[3]) * g1[3]);
;                 *(u32x4*)rowp = w;
.LBB0_447:
	v_and_b32_e32 v149, 63, v163
	v_and_b32_e32 v150, 3, v149
	v_lshrrev_b32_e32 v151, 2, v149
	v_lshl_add_u32 v149, v150, 4, v151
	v_lshlrev_b32_e32 v149, 2, v149
	v_and_b32_e32 v148, 64, v142
	v_add_u32_e32 v148, v148, v151
	v_lshl_add_u32 v148, s62, 8, v148
	v_and_b32_e32 v140, 0x60, v146
	v_lshl_add_u32 v140, v150, 3, v140
	v_lshl_add_u32 v140, s63, 7, v140
	v_lshlrev_b32_e32 v140, 1, v140
	v_mad_u32_u24 v148, v148, s39, v140
	v_pk_mul_f32 v[188:189], v[124:125], s[46:47] op_sel_hi:[1,0]
	v_pk_mul_f32 v[190:191], v[126:127], s[46:47] op_sel_hi:[1,0]
	v_pk_mul_f32 v[192:193], v[116:117], s[46:47] op_sel_hi:[1,0]
	v_pk_mul_f32 v[194:195], v[118:119], s[46:47] op_sel_hi:[1,0]
	v_pk_mul_f32 v[196:197], v[108:109], s[46:47] op_sel_hi:[1,0]
	v_pk_mul_f32 v[198:199], v[110:111], s[46:47] op_sel_hi:[1,0]
	v_pk_mul_f32 v[200:201], v[100:101], s[46:47] op_sel_hi:[1,0]
	v_pk_mul_f32 v[202:203], v[102:103], s[46:47] op_sel_hi:[1,0]
	v_exp_f32_e32 v188, v188
	v_exp_f32_e32 v189, v189
	v_exp_f32_e32 v190, v190
	v_exp_f32_e32 v191, v191
	v_exp_f32_e32 v192, v192
	v_exp_f32_e32 v193, v193
	v_exp_f32_e32 v194, v194
	v_exp_f32_e32 v195, v195
	v_exp_f32_e32 v196, v196
	v_exp_f32_e32 v197, v197
	v_exp_f32_e32 v198, v198
	v_exp_f32_e32 v199, v199
	v_exp_f32_e32 v200, v200
	v_exp_f32_e32 v201, v201
	v_exp_f32_e32 v202, v202
	v_exp_f32_e32 v203, v203
	v_pk_add_f32 v[188:189], v[188:189], 1.0 op_sel_hi:[1,0]
	v_pk_add_f32 v[190:191], v[190:191], 1.0 op_sel_hi:[1,0]
	v_pk_add_f32 v[192:193], v[192:193], 1.0 op_sel_hi:[1,0]
	v_pk_add_f32 v[194:195], v[194:195], 1.0 op_sel_hi:[1,0]
	v_pk_add_f32 v[196:197], v[196:197], 1.0 op_sel_hi:[1,0]
	v_pk_add_f32 v[198:199], v[198:199], 1.0 op_sel_hi:[1,0]
	v_pk_add_f32 v[200:201], v[200:201], 1.0 op_sel_hi:[1,0]
	v_pk_add_f32 v[202:203], v[202:203], 1.0 op_sel_hi:[1,0]
	v_rcp_f32_e32 v188, v188
	v_rcp_f32_e32 v189, v189
	v_rcp_f32_e32 v190, v190
	v_rcp_f32_e32 v191, v191
	v_rcp_f32_e32 v192, v192
	v_rcp_f32_e32 v193, v193
	v_rcp_f32_e32 v194, v194
	v_rcp_f32_e32 v195, v195
	v_rcp_f32_e32 v196, v196
	v_rcp_f32_e32 v197, v197
	v_rcp_f32_e32 v198, v198
	v_rcp_f32_e32 v199, v199
	v_rcp_f32_e32 v200, v200
	v_rcp_f32_e32 v201, v201
	v_rcp_f32_e32 v202, v202
	v_rcp_f32_e32 v203, v203
	v_pk_mul_f32 v[188:189], v[124:125], v[188:189]
	v_pk_mul_f32 v[190:191], v[126:127], v[190:191]
	v_pk_mul_f32 v[192:193], v[116:117], v[192:193]
	v_pk_mul_f32 v[194:195], v[118:119], v[194:195]
	v_pk_mul_f32 v[196:197], v[108:109], v[196:197]
	v_pk_mul_f32 v[198:199], v[110:111], v[198:199]
	v_pk_mul_f32 v[200:201], v[100:101], v[200:201]
	v_pk_mul_f32 v[202:203], v[102:103], v[202:203]
	v_pk_mul_f32 v[188:189], v[188:189], v[120:121]
	v_pk_mul_f32 v[190:191], v[190:191], v[122:123]
	v_pk_mul_f32 v[192:193], v[192:193], v[112:113]
	v_pk_mul_f32 v[194:195], v[194:195], v[114:115]
	v_pk_mul_f32 v[196:197], v[196:197], v[104:105]
	v_pk_mul_f32 v[198:199], v[198:199], v[106:107]
	v_pk_mul_f32 v[200:201], v[200:201], v[96:97]
	v_pk_mul_f32 v[202:203], v[202:203], v[98:99]
	v_cvt_pk_bf16_f32 v204, v188, v189
	v_cvt_pk_bf16_f32 v205, v190, v191
	v_cvt_pk_bf16_f32 v206, v192, v193
	v_cvt_pk_bf16_f32 v207, v194, v195
	v_cvt_pk_bf16_f32 v208, v196, v197
	v_cvt_pk_bf16_f32 v209, v198, v199
	v_cvt_pk_bf16_f32 v210, v200, v201
	v_cvt_pk_bf16_f32 v211, v202, v203
	ds_bpermute_b32 v212, v149, v204
	ds_bpermute_b32 v213, v149, v205
	ds_bpermute_b32 v214, v149, v206
	ds_bpermute_b32 v215, v149, v207
	ds_bpermute_b32 v216, v149, v208
	ds_bpermute_b32 v217, v149, v209
	ds_bpermute_b32 v218, v149, v210
	ds_bpermute_b32 v219, v149, v211
	v_pk_mul_f32 v[188:189], v[92:93], s[46:47] op_sel_hi:[1,0]
	v_pk_mul_f32 v[190:191], v[94:95], s[46:47] op_sel_hi:[1,0]
	v_pk_mul_f32 v[192:193], v[84:85], s[46:47] op_sel_hi:[1,0]
	v_pk_mul_f32 v[194:195], v[86:87], s[46:47] op_sel_hi:[1,0]
	v_pk_mul_f32 v[196:197], v[76:77], s[46:47] op_sel_hi:[1,0]
	v_pk_mul_f32 v[198:199], v[78:79], s[46:47] op_sel_hi:[1,0]
	v_pk_mul_f32 v[200:201], v[68:69], s[46:47] op_sel_hi:[1,0]
	v_pk_mul_f32 v[202:203], v[70:71], s[46:47] op_sel_hi:[1,0]
	v_exp_f32_e32 v188, v188
	v_exp_f32_e32 v189, v189
	v_exp_f32_e32 v190, v190
	v_exp_f32_e32 v191, v191
	v_exp_f32_e32 v192, v192
	v_exp_f32_e32 v193, v193
	v_exp_f32_e32 v194, v194
	v_exp_f32_e32 v195, v195
	v_exp_f32_e32 v196, v196
	v_exp_f32_e32 v197, v197
	v_exp_f32_e32 v198, v198
	v_exp_f32_e32 v199, v199
	v_exp_f32_e32 v200, v200
	v_exp_f32_e32 v201, v201
	v_exp_f32_e32 v202, v202
	v_exp_f32_e32 v203, v203
	v_pk_add_f32 v[188:189], v[188:189], 1.0 op_sel_hi:[1,0]
	v_pk_add_f32 v[190:191], v[190:191], 1.0 op_sel_hi:[1,0]
	v_pk_add_f32 v[192:193], v[192:193], 1.0 op_sel_hi:[1,0]
	v_pk_add_f32 v[194:195], v[194:195], 1.0 op_sel_hi:[1,0]
	v_pk_add_f32 v[196:197], v[196:197], 1.0 op_sel_hi:[1,0]
	v_pk_add_f32 v[198:199], v[198:199], 1.0 op_sel_hi:[1,0]
	v_pk_add_f32 v[200:201], v[200:201], 1.0 op_sel_hi:[1,0]
	v_pk_add_f32 v[202:203], v[202:203], 1.0 op_sel_hi:[1,0]
	v_rcp_f32_e32 v188, v188
	v_rcp_f32_e32 v189, v189
	v_rcp_f32_e32 v190, v190
	v_rcp_f32_e32 v191, v191
	v_rcp_f32_e32 v192, v192
	v_rcp_f32_e32 v193, v193
	v_rcp_f32_e32 v194, v194
	v_rcp_f32_e32 v195, v195
	v_rcp_f32_e32 v196, v196
	v_rcp_f32_e32 v197, v197
	v_rcp_f32_e32 v198, v198
	v_rcp_f32_e32 v199, v199
	v_rcp_f32_e32 v200, v200
	v_rcp_f32_e32 v201, v201
	v_rcp_f32_e32 v202, v202
	v_rcp_f32_e32 v203, v203
	v_pk_mul_f32 v[188:189], v[92:93], v[188:189]
	v_pk_mul_f32 v[190:191], v[94:95], v[190:191]
	v_pk_mul_f32 v[192:193], v[84:85], v[192:193]
	v_pk_mul_f32 v[194:195], v[86:87], v[194:195]
	v_pk_mul_f32 v[196:197], v[76:77], v[196:197]
	v_pk_mul_f32 v[198:199], v[78:79], v[198:199]
	v_pk_mul_f32 v[200:201], v[68:69], v[200:201]
	v_pk_mul_f32 v[202:203], v[70:71], v[202:203]
	v_pk_mul_f32 v[188:189], v[188:189], v[88:89]
	v_pk_mul_f32 v[190:191], v[190:191], v[90:91]
	v_pk_mul_f32 v[192:193], v[192:193], v[80:81]
	v_pk_mul_f32 v[194:195], v[194:195], v[82:83]
	v_pk_mul_f32 v[196:197], v[196:197], v[72:73]
	v_pk_mul_f32 v[198:199], v[198:199], v[74:75]
	v_pk_mul_f32 v[200:201], v[200:201], v[64:65]
	v_pk_mul_f32 v[202:203], v[202:203], v[66:67]
	s_waitcnt lgkmcnt(0)
; __device__ __forceinline__ unsigned pk2(float lo, float hi) { return pg8::cvt_pk_bf16(lo, hi); }
; __device__ __forceinline__ float siluf_(float x) { return x * sigmoidf_(x); }
;     __device__ __forceinline__ void operator()(const f32x4 (&acc)[2][2][4][2], const pg8::Unit& u, int wr, int wc, int fr, int fq) const {
;     ...
;             for (int m = 0; m < 4; ++m) {
;                 bf16_t* rowp = O + (size_t)(row0 + ai * 128 + m * 16) * ldc + col0;
;                 const f32x4 a0 = acc[ai][0][m][0], a1 = acc[ai][0][m][1], g0 = acc[ai][1][m][0], g1 = acc[ai][1][m][1];
;                 u32x4 w;
;                 w.x = pk2(siluf_(a0[0]) * g0[0], siluf_(a0[1]) * g0[1]); w.y = pk2(siluf_(a0[2]) * g0[2], siluf_(a0[3]) * g0[3]);
;                 w.z = pk2(siluf_(a1[0]) * g1[0], siluf_(a1[1]) * g1[1]); w.w = pk2(siluf_(a1[2]) * g1[2], siluf_(a1[3]) * g1[3]);
;                 *(u32x4*)rowp = w;
	global_store_dwordx4 v148, v[212:215], s[58:59]
	v_add_u32_e32 v148, 0x16000, v148
	global_store_dwordx4 v148, v[216:219], s[58:59]
	v_add_u32_e32 v148, 0x16000, v148
	v_cvt_pk_bf16_f32 v204, v188, v189
	v_cvt_pk_bf16_f32 v205, v190, v191
	v_cvt_pk_bf16_f32 v206, v192, v193
	v_cvt_pk_bf16_f32 v207, v194, v195
	v_cvt_pk_bf16_f32 v208, v196, v197
	v_cvt_pk_bf16_f32 v209, v198, v199
	v_cvt_pk_bf16_f32 v210, v200, v201
	v_cvt_pk_bf16_f32 v211, v202, v203
	ds_bpermute_b32 v212, v149, v204
	ds_bpermute_b32 v213, v149, v205
	ds_bpermute_b32 v214, v149, v206
	ds_bpermute_b32 v215, v149, v207
	ds_bpermute_b32 v216, v149, v208
	ds_bpermute_b32 v217, v149, v209
	ds_bpermute_b32 v218, v149, v210
	ds_bpermute_b32 v219, v149, v211
	v_pk_mul_f32 v[188:189], v[60:61], s[46:47] op_sel_hi:[1,0]
	v_pk_mul_f32 v[190:191], v[62:63], s[46:47] op_sel_hi:[1,0]
	v_pk_mul_f32 v[192:193], v[52:53], s[46:47] op_sel_hi:[1,0]
	v_pk_mul_f32 v[194:195], v[54:55], s[46:47] op_sel_hi:[1,0]
	v_pk_mul_f32 v[196:197], v[44:45], s[46:47] op_sel_hi:[1,0]
	v_pk_mul_f32 v[198:199], v[46:47], s[46:47] op_sel_hi:[1,0]
	v_pk_mul_f32 v[200:201], v[36:37], s[46:47] op_sel_hi:[1,0]
	v_pk_mul_f32 v[202:203], v[38:39], s[46:47] op_sel_hi:[1,0]
	v_exp_f32_e32 v188, v188
	v_exp_f32_e32 v189, v189
	v_exp_f32_e32 v190, v190
	v_exp_f32_e32 v191, v191
	v_exp_f32_e32 v192, v192
	v_exp_f32_e32 v193, v193
	v_exp_f32_e32 v194, v194
	v_exp_f32_e32 v195, v195
	v_exp_f32_e32 v196, v196
	v_exp_f32_e32 v197, v197
	v_exp_f32_e32 v198, v198
	v_exp_f32_e32 v199, v199
	v_exp_f32_e32 v200, v200
	v_exp_f32_e32 v201, v201
	v_exp_f32_e32 v202, v202
	v_exp_f32_e32 v203, v203
	v_pk_add_f32 v[188:189], v[188:189], 1.0 op_sel_hi:[1,0]
	v_pk_add_f32 v[190:191], v[190:191], 1.0 op_sel_hi:[1,0]
	v_pk_add_f32 v[192:193], v[192:193], 1.0 op_sel_hi:[1,0]
	v_pk_add_f32 v[194:195], v[194:195], 1.0 op_sel_hi:[1,0]
	v_pk_add_f32 v[196:197], v[196:197], 1.0 op_sel_hi:[1,0]
	v_pk_add_f32 v[198:199], v[198:199], 1.0 op_sel_hi:[1,0]
	v_pk_add_f32 v[200:201], v[200:201], 1.0 op_sel_hi:[1,0]
	v_pk_add_f32 v[202:203], v[202:203], 1.0 op_sel_hi:[1,0]
	v_rcp_f32_e32 v188, v188
	v_rcp_f32_e32 v189, v189
	v_rcp_f32_e32 v190, v190
	v_rcp_f32_e32 v191, v191
	v_rcp_f32_e32 v192, v192
	v_rcp_f32_e32 v193, v193
	v_rcp_f32_e32 v194, v194
	v_rcp_f32_e32 v195, v195
	v_rcp_f32_e32 v196, v196
	v_rcp_f32_e32 v197, v197
	v_rcp_f32_e32 v198, v198
	v_rcp_f32_e32 v199, v199
	v_rcp_f32_e32 v200, v200
	v_rcp_f32_e32 v201, v201
	v_rcp_f32_e32 v202, v202
	v_rcp_f32_e32 v203, v203
	v_pk_mul_f32 v[188:189], v[60:61], v[188:189]
	v_pk_mul_f32 v[190:191], v[62:63], v[190:191]
	v_pk_mul_f32 v[192:193], v[52:53], v[192:193]
	v_pk_mul_f32 v[194:195], v[54:55], v[194:195]
	v_pk_mul_f32 v[196:197], v[44:45], v[196:197]
	v_pk_mul_f32 v[198:199], v[46:47], v[198:199]
	v_pk_mul_f32 v[200:201], v[36:37], v[200:201]
	v_pk_mul_f32 v[202:203], v[38:39], v[202:203]
	v_pk_mul_f32 v[188:189], v[188:189], v[56:57]
	v_pk_mul_f32 v[190:191], v[190:191], v[58:59]
	v_pk_mul_f32 v[192:193], v[192:193], v[48:49]
	v_pk_mul_f32 v[194:195], v[194:195], v[50:51]
	v_pk_mul_f32 v[196:197], v[196:197], v[40:41]
	v_pk_mul_f32 v[198:199], v[198:199], v[42:43]
	v_pk_mul_f32 v[200:201], v[200:201], v[32:33]
	v_pk_mul_f32 v[202:203], v[202:203], v[34:35]
	s_waitcnt lgkmcnt(0)
; #define PG8_BAR __builtin_amdgcn_s_barrier()
; __device__ __forceinline__ unsigned pk2(float lo, float hi) { return pg8::cvt_pk_bf16(lo, hi); }
; __device__ __forceinline__ float siluf_(float x) { return x * sigmoidf_(x); }
; template <class Epi, class Sched, bool ALIGN_EPI = false, bool SP2 = false>
; __device__ __forceinline__ void gemm_phase(PG8_LAS unsigned char* lds, const Gemm g, const Sched& S, const Epi& E) {
;     ...
;         if (!has_next) break;
; #pragma unroll
;         for (int a = 0; a < 2; ++a)
; #pragma unroll
;             for (int b = 0; b < 2; ++b)
; #pragma unroll
;                 for (int m = 0; m < 4; ++m)
; #pragma unroll
;                     for (int n = 0; n < 2; ++n) acc[a][b][m][n] = (f32x4){0.f, 0.f, 0.f, 0.f};
;         cur = nxt; cA = nA; cB = nB; ++ui;
;         if constexpr (ALIGN_EPI) { if (wr == 1) PG8_BAR; }
;     __device__ __forceinline__ void operator()(const f32x4 (&acc)[2][2][4][2], const pg8::Unit& u, int wr, int wc, int fr, int fq) const {
;     ...
;             for (int m = 0; m < 4; ++m) {
;                 bf16_t* rowp = O + (size_t)(row0 + ai * 128 + m * 16) * ldc + col0;
;                 const f32x4 a0 = acc[ai][0][m][0], a1 = acc[ai][0][m][1], g0 = acc[ai][1][m][0], g1 = acc[ai][1][m][1];
;                 u32x4 w;
;                 w.x = pk2(siluf_(a0[0]) * g0[0], siluf_(a0[1]) * g0[1]); w.y = pk2(siluf_(a0[2]) * g0[2], siluf_(a0[3]) * g0[3]);
;                 w.z = pk2(siluf_(a1[0]) * g1[0], siluf_(a1[1]) * g1[1]); w.w = pk2(siluf_(a1[2]) * g1[2], siluf_(a1[3]) * g1[3]);
;                 *(u32x4*)rowp = w;
	global_store_dwordx4 v148, v[212:215], s[58:59]
	v_add_u32_e32 v148, 0x16000, v148
	global_store_dwordx4 v148, v[216:219], s[58:59]
	v_add_u32_e32 v148, 0x6e000, v148
	v_cvt_pk_bf16_f32 v204, v188, v189
	v_cvt_pk_bf16_f32 v205, v190, v191
	v_cvt_pk_bf16_f32 v206, v192, v193
	v_cvt_pk_bf16_f32 v207, v194, v195
	v_cvt_pk_bf16_f32 v208, v196, v197
	v_cvt_pk_bf16_f32 v209, v198, v199
	v_cvt_pk_bf16_f32 v210, v200, v201
	v_cvt_pk_bf16_f32 v211, v202, v203
	ds_bpermute_b32 v212, v149, v204
	ds_bpermute_b32 v213, v149, v205
	ds_bpermute_b32 v214, v149, v206
	ds_bpermute_b32 v215, v149, v207
	ds_bpermute_b32 v216, v149, v208
	ds_bpermute_b32 v217, v149, v209
	ds_bpermute_b32 v218, v149, v210
	ds_bpermute_b32 v219, v149, v211
	v_pk_mul_f32 v[188:189], v[28:29], s[46:47] op_sel_hi:[1,0]
	v_pk_mul_f32 v[190:191], v[30:31], s[46:47] op_sel_hi:[1,0]
	v_pk_mul_f32 v[192:193], v[20:21], s[46:47] op_sel_hi:[1,0]
	v_pk_mul_f32 v[194:195], v[22:23], s[46:47] op_sel_hi:[1,0]
	v_pk_mul_f32 v[196:197], v[12:13], s[46:47] op_sel_hi:[1,0]
	v_pk_mul_f32 v[198:199], v[14:15], s[46:47] op_sel_hi:[1,0]
	v_pk_mul_f32 v[200:201], v[4:5], s[46:47] op_sel_hi:[1,0]
	v_pk_mul_f32 v[202:203], v[6:7], s[46:47] op_sel_hi:[1,0]
	v_exp_f32_e32 v188, v188
	v_exp_f32_e32 v189, v189
	v_exp_f32_e32 v190, v190
	v_exp_f32_e32 v191, v191
	v_exp_f32_e32 v192, v192
	v_exp_f32_e32 v193, v193
	v_exp_f32_e32 v194, v194
	v_exp_f32_e32 v195, v195
	v_exp_f32_e32 v196, v196
	v_exp_f32_e32 v197, v197
	v_exp_f32_e32 v198, v198
	v_exp_f32_e32 v199, v199
	v_exp_f32_e32 v200, v200
	v_exp_f32_e32 v201, v201
	v_exp_f32_e32 v202, v202
	v_exp_f32_e32 v203, v203
	v_pk_add_f32 v[188:189], v[188:189], 1.0 op_sel_hi:[1,0]
	v_pk_add_f32 v[190:191], v[190:191], 1.0 op_sel_hi:[1,0]
	v_pk_add_f32 v[192:193], v[192:193], 1.0 op_sel_hi:[1,0]
	v_pk_add_f32 v[194:195], v[194:195], 1.0 op_sel_hi:[1,0]
	v_pk_add_f32 v[196:197], v[196:197], 1.0 op_sel_hi:[1,0]
	v_pk_add_f32 v[198:199], v[198:199], 1.0 op_sel_hi:[1,0]
	v_pk_add_f32 v[200:201], v[200:201], 1.0 op_sel_hi:[1,0]
	v_pk_add_f32 v[202:203], v[202:203], 1.0 op_sel_hi:[1,0]
	v_rcp_f32_e32 v188, v188
	v_rcp_f32_e32 v189, v189
	v_rcp_f32_e32 v190, v190
	v_rcp_f32_e32 v191, v191
	v_rcp_f32_e32 v192, v192
	v_rcp_f32_e32 v193, v193
	v_rcp_f32_e32 v194, v194
	v_rcp_f32_e32 v195, v195
	v_rcp_f32_e32 v196, v196
	v_rcp_f32_e32 v197, v197
	v_rcp_f32_e32 v198, v198
	v_rcp_f32_e32 v199, v199
	v_rcp_f32_e32 v200, v200
	v_rcp_f32_e32 v201, v201
	v_rcp_f32_e32 v202, v202
	v_rcp_f32_e32 v203, v203
	v_pk_mul_f32 v[188:189], v[28:29], v[188:189]
	v_pk_mul_f32 v[190:191], v[30:31], v[190:191]
	v_pk_mul_f32 v[192:193], v[20:21], v[192:193]
	v_pk_mul_f32 v[194:195], v[22:23], v[194:195]
	v_pk_mul_f32 v[196:197], v[12:13], v[196:197]
	v_pk_mul_f32 v[198:199], v[14:15], v[198:199]
	v_pk_mul_f32 v[200:201], v[4:5], v[200:201]
	v_pk_mul_f32 v[202:203], v[6:7], v[202:203]
	v_pk_mul_f32 v[188:189], v[188:189], v[24:25]
	v_pk_mul_f32 v[190:191], v[190:191], v[26:27]
	v_pk_mul_f32 v[192:193], v[192:193], v[16:17]
	v_pk_mul_f32 v[194:195], v[194:195], v[18:19]
	v_pk_mul_f32 v[196:197], v[196:197], v[8:9]
	v_pk_mul_f32 v[198:199], v[198:199], v[10:11]
	v_pk_mul_f32 v[200:201], v[200:201], v[0:1]
	v_pk_mul_f32 v[202:203], v[202:203], v[2:3]
	s_waitcnt lgkmcnt(0)
	global_store_dwordx4 v148, v[212:215], s[58:59]
	v_add_u32_e32 v148, 0x16000, v148
	global_store_dwordx4 v148, v[216:219], s[58:59]
	v_add_u32_e32 v148, 0x16000, v148
	v_cvt_pk_bf16_f32 v204, v188, v189
	v_cvt_pk_bf16_f32 v205, v190, v191
	v_cvt_pk_bf16_f32 v206, v192, v193
	v_cvt_pk_bf16_f32 v207, v194, v195
	v_cvt_pk_bf16_f32 v208, v196, v197
	v_cvt_pk_bf16_f32 v209, v198, v199
	v_cvt_pk_bf16_f32 v210, v200, v201
	v_cvt_pk_bf16_f32 v211, v202, v203
	ds_bpermute_b32 v212, v149, v204
	ds_bpermute_b32 v213, v149, v205
	ds_bpermute_b32 v214, v149, v206
	ds_bpermute_b32 v215, v149, v207
	ds_bpermute_b32 v216, v149, v208
	ds_bpermute_b32 v217, v149, v209
	ds_bpermute_b32 v218, v149, v210
	ds_bpermute_b32 v219, v149, v211
	s_waitcnt lgkmcnt(0)
	global_store_dwordx4 v148, v[212:215], s[58:59]
	v_add_u32_e32 v148, 0x16000, v148
	global_store_dwordx4 v148, v[216:219], s[58:59]
	s_mov_b64 s[62:63], -1
	s_andn2_b64 vcc, exec, s[8:9]
	s_cbranch_vccnz .LBB0_440
	s_andn2_b64 vcc, exec, s[10:11]
	s_cbranch_vccnz .LBB0_439
	s_barrier
	s_branch .LBB0_439
